# P2 S5 output-GEMM epilogue: gelu evaluated in place with packed f32 ops (y*rcp(1+exp2(y*(a+b*y^2)))), 13-op dependent chain per value removed
# speedup vs baseline: 1.0124x; 1.0019x over previous
.LBB0_495:
	v_mov_b32_e32 v204, 0xbdd2d3e7
	v_mov_b32_e32 v206, 0xc0135761
	v_mov_b32_e32 v137, v136
	v_readlane_b32 s4, v254, 4
	v_ashrrev_i32_e32 v128, 2, v137
	v_and_b32_e32 v128, 0xffffffc0, v128
	v_and_or_b32 v129, v137, 15, s3
	s_lshl_b32 s0, s0, 5
	v_readlane_b32 s18, v254, 18
	v_add_u32_e32 v130, v129, v128
	v_readlane_b32 s19, v254, 19
	s_add_u32 s0, s18, s0
	v_lshrrev_b32_e32 v128, 1, v137
	s_addc_u32 s1, s19, 0
	v_and_b32_e32 v128, 24, v128
	v_mov_b32_e32 v129, 0
	v_lshl_add_u64 v[132:133], s[0:1], 0, v[128:129]
	v_ashrrev_i32_e32 v131, 31, v130
	v_lshlrev_b64 v[134:135], 14, v[130:131]
	v_lshl_add_u64 v[134:135], v[132:133], 0, v[134:135]
	s_movk_i32 s0, 0x2000
	v_readlane_b32 s5, v254, 5
	v_readlane_b32 s6, v254, 6
	v_readlane_b32 s7, v254, 7
	v_readlane_b32 s8, v254, 8
	v_readlane_b32 s9, v254, 9
	v_readlane_b32 s10, v254, 10
	v_pk_mul_f32 v[200:201], v[124:125], v[124:125]
	v_pk_mul_f32 v[202:203], v[126:127], v[126:127]
	v_pk_fma_f32 v[200:201], v[200:201], v[204:205], v[206:207] op_sel_hi:[1,0,0]
	v_pk_fma_f32 v[202:203], v[202:203], v[204:205], v[206:207] op_sel_hi:[1,0,0]
	v_pk_mul_f32 v[200:201], v[200:201], v[124:125]
	v_pk_mul_f32 v[202:203], v[202:203], v[126:127]
	v_exp_f32_e32 v200, v200
	v_exp_f32_e32 v201, v201
	v_exp_f32_e32 v202, v202
	v_exp_f32_e32 v203, v203
	s_nop 0
	v_pk_add_f32 v[200:201], v[200:201], 1.0 op_sel_hi:[1,0]
	v_pk_add_f32 v[202:203], v[202:203], 1.0 op_sel_hi:[1,0]
	v_rcp_f32_e32 v200, v200
	v_rcp_f32_e32 v201, v201
	v_rcp_f32_e32 v202, v202
	v_rcp_f32_e32 v203, v203
	s_nop 0
	v_pk_mul_f32 v[124:125], v[124:125], v[200:201]
	v_pk_mul_f32 v[126:127], v[126:127], v[202:203]
	v_cvt_pk_bf16_f32 v208, v124, v125
	v_cvt_pk_bf16_f32 v209, v126, v127
	v_readlane_b32 s11, v254, 11
	v_readlane_b32 s12, v254, 12
	v_readlane_b32 s13, v254, 13
	v_readlane_b32 s14, v254, 14
	v_readlane_b32 s15, v254, 15
	v_readlane_b32 s16, v254, 16
	v_readlane_b32 s17, v254, 17
	v_lshlrev_b32_e32 v124, 5, v137
	v_and_b32_e32 v128, 0x1800, v124
	v_lshl_add_u64 v[124:125], v[134:135], 0, v[128:129]
	v_mov_b32_e32 v126, v208
	v_mov_b32_e32 v127, v209
	global_store_dwordx2 v[124:125], v[126:127], off
	s_nop 0
	s_nop 0
	s_nop 0
	s_nop 0
	v_pk_mul_f32 v[200:201], v[120:121], v[120:121]
	v_pk_mul_f32 v[202:203], v[122:123], v[122:123]
	v_pk_fma_f32 v[200:201], v[200:201], v[204:205], v[206:207] op_sel_hi:[1,0,0]
	v_pk_fma_f32 v[202:203], v[202:203], v[204:205], v[206:207] op_sel_hi:[1,0,0]
	v_pk_mul_f32 v[200:201], v[200:201], v[120:121]
	v_pk_mul_f32 v[202:203], v[202:203], v[122:123]
	v_exp_f32_e32 v200, v200
	v_exp_f32_e32 v201, v201
	v_exp_f32_e32 v202, v202
	v_exp_f32_e32 v203, v203
	s_nop 0
	v_pk_add_f32 v[200:201], v[200:201], 1.0 op_sel_hi:[1,0]
	v_pk_add_f32 v[202:203], v[202:203], 1.0 op_sel_hi:[1,0]
	v_rcp_f32_e32 v200, v200
	v_rcp_f32_e32 v201, v201
	v_rcp_f32_e32 v202, v202
	v_rcp_f32_e32 v203, v203
	s_nop 0
	v_pk_mul_f32 v[120:121], v[120:121], v[200:201]
	v_pk_mul_f32 v[122:123], v[122:123], v[202:203]
	v_cvt_pk_bf16_f32 v208, v120, v121
	v_cvt_pk_bf16_f32 v209, v122, v123
	v_add_co_u32_e32 v120, vcc, s0, v124
	s_nop 1
	v_addc_co_u32_e32 v121, vcc, 0, v125, vcc
	v_mov_b32_e32 v122, v208
	v_mov_b32_e32 v123, v209
	global_store_dwordx2 v[120:121], v[122:123], off
	s_nop 0
	s_nop 0
	v_pk_mul_f32 v[200:201], v[116:117], v[116:117]
	v_pk_mul_f32 v[202:203], v[118:119], v[118:119]
	v_pk_fma_f32 v[200:201], v[200:201], v[204:205], v[206:207] op_sel_hi:[1,0,0]
	v_pk_fma_f32 v[202:203], v[202:203], v[204:205], v[206:207] op_sel_hi:[1,0,0]
	v_pk_mul_f32 v[200:201], v[200:201], v[116:117]
	v_pk_mul_f32 v[202:203], v[202:203], v[118:119]
	v_exp_f32_e32 v200, v200
	v_exp_f32_e32 v201, v201
	v_exp_f32_e32 v202, v202
	v_exp_f32_e32 v203, v203
	s_nop 0
	v_pk_add_f32 v[200:201], v[200:201], 1.0 op_sel_hi:[1,0]
	v_pk_add_f32 v[202:203], v[202:203], 1.0 op_sel_hi:[1,0]
	v_rcp_f32_e32 v200, v200
	v_rcp_f32_e32 v201, v201
	v_rcp_f32_e32 v202, v202
	v_rcp_f32_e32 v203, v203
	s_nop 0
	v_pk_mul_f32 v[116:117], v[116:117], v[200:201]
	v_pk_mul_f32 v[118:119], v[118:119], v[202:203]
	v_cvt_pk_bf16_f32 v208, v116, v117
	v_cvt_pk_bf16_f32 v209, v118, v119
	s_nop 0
	s_nop 0
	v_mov_b32_e32 v116, v208
	v_mov_b32_e32 v117, v209
	global_store_dwordx2 v[124:125], v[116:117], off offset:1024
	s_nop 0
	s_nop 0
	v_pk_mul_f32 v[200:201], v[112:113], v[112:113]
	v_pk_mul_f32 v[202:203], v[114:115], v[114:115]
	v_pk_fma_f32 v[200:201], v[200:201], v[204:205], v[206:207] op_sel_hi:[1,0,0]
	v_pk_fma_f32 v[202:203], v[202:203], v[204:205], v[206:207] op_sel_hi:[1,0,0]
	v_pk_mul_f32 v[200:201], v[200:201], v[112:113]
	v_pk_mul_f32 v[202:203], v[202:203], v[114:115]
	v_exp_f32_e32 v200, v200
	v_exp_f32_e32 v201, v201
	v_exp_f32_e32 v202, v202
	v_exp_f32_e32 v203, v203
	s_nop 0
	v_pk_add_f32 v[200:201], v[200:201], 1.0 op_sel_hi:[1,0]
	v_pk_add_f32 v[202:203], v[202:203], 1.0 op_sel_hi:[1,0]
	v_rcp_f32_e32 v200, v200
	v_rcp_f32_e32 v201, v201
	v_rcp_f32_e32 v202, v202
	v_rcp_f32_e32 v203, v203
	s_nop 0
	v_pk_mul_f32 v[112:113], v[112:113], v[200:201]
	v_pk_mul_f32 v[114:115], v[114:115], v[202:203]
	v_cvt_pk_bf16_f32 v208, v112, v113
	v_cvt_pk_bf16_f32 v209, v114, v115
	s_nop 0
	s_nop 0
	v_mov_b32_e32 v112, v208
	v_mov_b32_e32 v113, v209
	global_store_dwordx2 v[120:121], v[112:113], off offset:1024
	v_or_b32_e32 v112, 16, v130
	v_ashrrev_i32_e32 v113, 31, v112
	v_lshlrev_b64 v[112:113], 14, v[112:113]
	v_lshl_add_u64 v[112:113], v[132:133], 0, v[112:113]
	s_nop 0
	v_pk_mul_f32 v[200:201], v[108:109], v[108:109]
	v_pk_mul_f32 v[202:203], v[110:111], v[110:111]
	v_pk_fma_f32 v[200:201], v[200:201], v[204:205], v[206:207] op_sel_hi:[1,0,0]
	v_pk_fma_f32 v[202:203], v[202:203], v[204:205], v[206:207] op_sel_hi:[1,0,0]
	v_pk_mul_f32 v[200:201], v[200:201], v[108:109]
	v_pk_mul_f32 v[202:203], v[202:203], v[110:111]
	v_exp_f32_e32 v200, v200
	v_exp_f32_e32 v201, v201
	v_exp_f32_e32 v202, v202
	v_exp_f32_e32 v203, v203
	s_nop 0
	v_pk_add_f32 v[200:201], v[200:201], 1.0 op_sel_hi:[1,0]
	v_pk_add_f32 v[202:203], v[202:203], 1.0 op_sel_hi:[1,0]
	v_rcp_f32_e32 v200, v200
	v_rcp_f32_e32 v201, v201
	v_rcp_f32_e32 v202, v202
	v_rcp_f32_e32 v203, v203
	s_nop 0
	v_pk_mul_f32 v[108:109], v[108:109], v[200:201]
	v_pk_mul_f32 v[110:111], v[110:111], v[202:203]
	v_cvt_pk_bf16_f32 v208, v108, v109
	v_cvt_pk_bf16_f32 v209, v110, v111
	s_nop 0
	s_nop 0
	v_lshl_add_u64 v[108:109], v[112:113], 0, v[128:129]
	v_mov_b32_e32 v110, v208
	v_mov_b32_e32 v111, v209
	global_store_dwordx2 v[108:109], v[110:111], off
	s_nop 0
	s_nop 0
	s_nop 0
	s_nop 0
	v_pk_mul_f32 v[200:201], v[104:105], v[104:105]
	v_pk_mul_f32 v[202:203], v[106:107], v[106:107]
	v_pk_fma_f32 v[200:201], v[200:201], v[204:205], v[206:207] op_sel_hi:[1,0,0]
	v_pk_fma_f32 v[202:203], v[202:203], v[204:205], v[206:207] op_sel_hi:[1,0,0]
	v_pk_mul_f32 v[200:201], v[200:201], v[104:105]
	v_pk_mul_f32 v[202:203], v[202:203], v[106:107]
	v_exp_f32_e32 v200, v200
	v_exp_f32_e32 v201, v201
	v_exp_f32_e32 v202, v202
	v_exp_f32_e32 v203, v203
	s_nop 0
	v_pk_add_f32 v[200:201], v[200:201], 1.0 op_sel_hi:[1,0]
	v_pk_add_f32 v[202:203], v[202:203], 1.0 op_sel_hi:[1,0]
	v_rcp_f32_e32 v200, v200
	v_rcp_f32_e32 v201, v201
	v_rcp_f32_e32 v202, v202
	v_rcp_f32_e32 v203, v203
	s_nop 0
	v_pk_mul_f32 v[104:105], v[104:105], v[200:201]
	v_pk_mul_f32 v[106:107], v[106:107], v[202:203]
	v_cvt_pk_bf16_f32 v208, v104, v105
	v_cvt_pk_bf16_f32 v209, v106, v107
	v_add_co_u32_e32 v104, vcc, s0, v108
	s_nop 1
	v_addc_co_u32_e32 v105, vcc, 0, v109, vcc
	v_mov_b32_e32 v106, v208
	v_mov_b32_e32 v107, v209
	global_store_dwordx2 v[104:105], v[106:107], off
	s_nop 0
	s_nop 0
	v_pk_mul_f32 v[200:201], v[100:101], v[100:101]
	v_pk_mul_f32 v[202:203], v[102:103], v[102:103]
	v_pk_fma_f32 v[200:201], v[200:201], v[204:205], v[206:207] op_sel_hi:[1,0,0]
	v_pk_fma_f32 v[202:203], v[202:203], v[204:205], v[206:207] op_sel_hi:[1,0,0]
	v_pk_mul_f32 v[200:201], v[200:201], v[100:101]
	v_pk_mul_f32 v[202:203], v[202:203], v[102:103]
	v_exp_f32_e32 v200, v200
	v_exp_f32_e32 v201, v201
	v_exp_f32_e32 v202, v202
	v_exp_f32_e32 v203, v203
	s_nop 0
	v_pk_add_f32 v[200:201], v[200:201], 1.0 op_sel_hi:[1,0]
	v_pk_add_f32 v[202:203], v[202:203], 1.0 op_sel_hi:[1,0]
	v_rcp_f32_e32 v200, v200
	v_rcp_f32_e32 v201, v201
	v_rcp_f32_e32 v202, v202
	v_rcp_f32_e32 v203, v203
	s_nop 0
	v_pk_mul_f32 v[100:101], v[100:101], v[200:201]
	v_pk_mul_f32 v[102:103], v[102:103], v[202:203]
	v_cvt_pk_bf16_f32 v208, v100, v101
	v_cvt_pk_bf16_f32 v209, v102, v103
	s_nop 0
	s_nop 0
	v_mov_b32_e32 v100, v208
	v_mov_b32_e32 v101, v209
	global_store_dwordx2 v[108:109], v[100:101], off offset:1024
	s_nop 0
	s_nop 0
	v_pk_mul_f32 v[200:201], v[96:97], v[96:97]
	v_pk_mul_f32 v[202:203], v[98:99], v[98:99]
	v_pk_fma_f32 v[200:201], v[200:201], v[204:205], v[206:207] op_sel_hi:[1,0,0]
	v_pk_fma_f32 v[202:203], v[202:203], v[204:205], v[206:207] op_sel_hi:[1,0,0]
	v_pk_mul_f32 v[200:201], v[200:201], v[96:97]
	v_pk_mul_f32 v[202:203], v[202:203], v[98:99]
	v_exp_f32_e32 v200, v200
	v_exp_f32_e32 v201, v201
	v_exp_f32_e32 v202, v202
	v_exp_f32_e32 v203, v203
	s_nop 0
	v_pk_add_f32 v[200:201], v[200:201], 1.0 op_sel_hi:[1,0]
	v_pk_add_f32 v[202:203], v[202:203], 1.0 op_sel_hi:[1,0]
	v_rcp_f32_e32 v200, v200
	v_rcp_f32_e32 v201, v201
	v_rcp_f32_e32 v202, v202
	v_rcp_f32_e32 v203, v203
	s_nop 0
	v_pk_mul_f32 v[96:97], v[96:97], v[200:201]
	v_pk_mul_f32 v[98:99], v[98:99], v[202:203]
	v_cvt_pk_bf16_f32 v208, v96, v97
	v_cvt_pk_bf16_f32 v209, v98, v99
	s_nop 0
	s_nop 0
	v_mov_b32_e32 v96, v208
	v_mov_b32_e32 v97, v209
	global_store_dwordx2 v[104:105], v[96:97], off offset:1024
	v_or_b32_e32 v96, 32, v130
	v_ashrrev_i32_e32 v97, 31, v96
	v_lshlrev_b64 v[96:97], 14, v[96:97]
	v_lshl_add_u64 v[96:97], v[132:133], 0, v[96:97]
	s_nop 0
	v_pk_mul_f32 v[200:201], v[92:93], v[92:93]
	v_pk_mul_f32 v[202:203], v[94:95], v[94:95]
	v_pk_fma_f32 v[200:201], v[200:201], v[204:205], v[206:207] op_sel_hi:[1,0,0]
	v_pk_fma_f32 v[202:203], v[202:203], v[204:205], v[206:207] op_sel_hi:[1,0,0]
	v_pk_mul_f32 v[200:201], v[200:201], v[92:93]
	v_pk_mul_f32 v[202:203], v[202:203], v[94:95]
	v_exp_f32_e32 v200, v200
	v_exp_f32_e32 v201, v201
	v_exp_f32_e32 v202, v202
	v_exp_f32_e32 v203, v203
	s_nop 0
	v_pk_add_f32 v[200:201], v[200:201], 1.0 op_sel_hi:[1,0]
	v_pk_add_f32 v[202:203], v[202:203], 1.0 op_sel_hi:[1,0]
	v_rcp_f32_e32 v200, v200
	v_rcp_f32_e32 v201, v201
	v_rcp_f32_e32 v202, v202
	v_rcp_f32_e32 v203, v203
	s_nop 0
	v_pk_mul_f32 v[92:93], v[92:93], v[200:201]
	v_pk_mul_f32 v[94:95], v[94:95], v[202:203]
	v_cvt_pk_bf16_f32 v208, v92, v93
	v_cvt_pk_bf16_f32 v209, v94, v95
	s_nop 0
	s_nop 0
	v_lshl_add_u64 v[92:93], v[96:97], 0, v[128:129]
	v_mov_b32_e32 v94, v208
	v_mov_b32_e32 v95, v209
	global_store_dwordx2 v[92:93], v[94:95], off
	s_nop 0
	s_nop 0
	s_nop 0
	s_nop 0
	v_pk_mul_f32 v[200:201], v[88:89], v[88:89]
	v_pk_mul_f32 v[202:203], v[90:91], v[90:91]
	v_pk_fma_f32 v[200:201], v[200:201], v[204:205], v[206:207] op_sel_hi:[1,0,0]
	v_pk_fma_f32 v[202:203], v[202:203], v[204:205], v[206:207] op_sel_hi:[1,0,0]
	v_pk_mul_f32 v[200:201], v[200:201], v[88:89]
	v_pk_mul_f32 v[202:203], v[202:203], v[90:91]
	v_exp_f32_e32 v200, v200
	v_exp_f32_e32 v201, v201
	v_exp_f32_e32 v202, v202
	v_exp_f32_e32 v203, v203
	s_nop 0
	v_pk_add_f32 v[200:201], v[200:201], 1.0 op_sel_hi:[1,0]
	v_pk_add_f32 v[202:203], v[202:203], 1.0 op_sel_hi:[1,0]
	v_rcp_f32_e32 v200, v200
	v_rcp_f32_e32 v201, v201
	v_rcp_f32_e32 v202, v202
	v_rcp_f32_e32 v203, v203
	s_nop 0
	v_pk_mul_f32 v[88:89], v[88:89], v[200:201]
	v_pk_mul_f32 v[90:91], v[90:91], v[202:203]
	v_cvt_pk_bf16_f32 v208, v88, v89
	v_cvt_pk_bf16_f32 v209, v90, v91
	v_add_co_u32_e32 v88, vcc, s0, v92
	s_nop 1
	v_addc_co_u32_e32 v89, vcc, 0, v93, vcc
	v_mov_b32_e32 v90, v208
	v_mov_b32_e32 v91, v209
	global_store_dwordx2 v[88:89], v[90:91], off
	s_nop 0
	s_nop 0
	v_pk_mul_f32 v[200:201], v[84:85], v[84:85]
	v_pk_mul_f32 v[202:203], v[86:87], v[86:87]
	v_pk_fma_f32 v[200:201], v[200:201], v[204:205], v[206:207] op_sel_hi:[1,0,0]
	v_pk_fma_f32 v[202:203], v[202:203], v[204:205], v[206:207] op_sel_hi:[1,0,0]
	v_pk_mul_f32 v[200:201], v[200:201], v[84:85]
	v_pk_mul_f32 v[202:203], v[202:203], v[86:87]
	v_exp_f32_e32 v200, v200
	v_exp_f32_e32 v201, v201
	v_exp_f32_e32 v202, v202
	v_exp_f32_e32 v203, v203
	s_nop 0
	v_pk_add_f32 v[200:201], v[200:201], 1.0 op_sel_hi:[1,0]
	v_pk_add_f32 v[202:203], v[202:203], 1.0 op_sel_hi:[1,0]
	v_rcp_f32_e32 v200, v200
	v_rcp_f32_e32 v201, v201
	v_rcp_f32_e32 v202, v202
	v_rcp_f32_e32 v203, v203
	s_nop 0
	v_pk_mul_f32 v[84:85], v[84:85], v[200:201]
	v_pk_mul_f32 v[86:87], v[86:87], v[202:203]
	v_cvt_pk_bf16_f32 v208, v84, v85
	v_cvt_pk_bf16_f32 v209, v86, v87
	s_nop 0
	s_nop 0
	v_mov_b32_e32 v84, v208
	v_mov_b32_e32 v85, v209
	global_store_dwordx2 v[92:93], v[84:85], off offset:1024
	s_nop 0
	s_nop 0
	v_pk_mul_f32 v[200:201], v[80:81], v[80:81]
	v_pk_mul_f32 v[202:203], v[82:83], v[82:83]
	v_pk_fma_f32 v[200:201], v[200:201], v[204:205], v[206:207] op_sel_hi:[1,0,0]
	v_pk_fma_f32 v[202:203], v[202:203], v[204:205], v[206:207] op_sel_hi:[1,0,0]
	v_pk_mul_f32 v[200:201], v[200:201], v[80:81]
	v_pk_mul_f32 v[202:203], v[202:203], v[82:83]
	v_exp_f32_e32 v200, v200
	v_exp_f32_e32 v201, v201
	v_exp_f32_e32 v202, v202
	v_exp_f32_e32 v203, v203
	s_nop 0
	v_pk_add_f32 v[200:201], v[200:201], 1.0 op_sel_hi:[1,0]
	v_pk_add_f32 v[202:203], v[202:203], 1.0 op_sel_hi:[1,0]
	v_rcp_f32_e32 v200, v200
	v_rcp_f32_e32 v201, v201
	v_rcp_f32_e32 v202, v202
	v_rcp_f32_e32 v203, v203
	s_nop 0
	v_pk_mul_f32 v[80:81], v[80:81], v[200:201]
	v_pk_mul_f32 v[82:83], v[82:83], v[202:203]
	v_cvt_pk_bf16_f32 v208, v80, v81
	v_cvt_pk_bf16_f32 v209, v82, v83
	s_nop 0
	s_nop 0
	v_mov_b32_e32 v80, v208
	v_mov_b32_e32 v81, v209
	global_store_dwordx2 v[88:89], v[80:81], off offset:1024
	v_or_b32_e32 v80, 48, v130
	v_ashrrev_i32_e32 v81, 31, v80
	v_lshlrev_b64 v[80:81], 14, v[80:81]
	v_lshl_add_u64 v[80:81], v[132:133], 0, v[80:81]
	s_nop 0
	v_pk_mul_f32 v[200:201], v[76:77], v[76:77]
	v_pk_mul_f32 v[202:203], v[78:79], v[78:79]
	v_pk_fma_f32 v[200:201], v[200:201], v[204:205], v[206:207] op_sel_hi:[1,0,0]
	v_pk_fma_f32 v[202:203], v[202:203], v[204:205], v[206:207] op_sel_hi:[1,0,0]
	v_pk_mul_f32 v[200:201], v[200:201], v[76:77]
	v_pk_mul_f32 v[202:203], v[202:203], v[78:79]
	v_exp_f32_e32 v200, v200
	v_exp_f32_e32 v201, v201
	v_exp_f32_e32 v202, v202
	v_exp_f32_e32 v203, v203
	s_nop 0
	v_pk_add_f32 v[200:201], v[200:201], 1.0 op_sel_hi:[1,0]
	v_pk_add_f32 v[202:203], v[202:203], 1.0 op_sel_hi:[1,0]
	v_rcp_f32_e32 v200, v200
	v_rcp_f32_e32 v201, v201
	v_rcp_f32_e32 v202, v202
	v_rcp_f32_e32 v203, v203
	s_nop 0
	v_pk_mul_f32 v[76:77], v[76:77], v[200:201]
	v_pk_mul_f32 v[78:79], v[78:79], v[202:203]
	v_cvt_pk_bf16_f32 v208, v76, v77
	v_cvt_pk_bf16_f32 v209, v78, v79
	s_nop 0
	s_nop 0
	v_lshl_add_u64 v[76:77], v[80:81], 0, v[128:129]
	v_mov_b32_e32 v78, v208
	v_mov_b32_e32 v79, v209
	global_store_dwordx2 v[76:77], v[78:79], off
	s_nop 0
	s_nop 0
	s_nop 0
	s_nop 0
	v_pk_mul_f32 v[200:201], v[72:73], v[72:73]
	v_pk_mul_f32 v[202:203], v[74:75], v[74:75]
	v_pk_fma_f32 v[200:201], v[200:201], v[204:205], v[206:207] op_sel_hi:[1,0,0]
	v_pk_fma_f32 v[202:203], v[202:203], v[204:205], v[206:207] op_sel_hi:[1,0,0]
	v_pk_mul_f32 v[200:201], v[200:201], v[72:73]
	v_pk_mul_f32 v[202:203], v[202:203], v[74:75]
	v_exp_f32_e32 v200, v200
	v_exp_f32_e32 v201, v201
	v_exp_f32_e32 v202, v202
	v_exp_f32_e32 v203, v203
	s_nop 0
	v_pk_add_f32 v[200:201], v[200:201], 1.0 op_sel_hi:[1,0]
	v_pk_add_f32 v[202:203], v[202:203], 1.0 op_sel_hi:[1,0]
	v_rcp_f32_e32 v200, v200
	v_rcp_f32_e32 v201, v201
	v_rcp_f32_e32 v202, v202
	v_rcp_f32_e32 v203, v203
	s_nop 0
	v_pk_mul_f32 v[72:73], v[72:73], v[200:201]
	v_pk_mul_f32 v[74:75], v[74:75], v[202:203]
	v_cvt_pk_bf16_f32 v208, v72, v73
	v_cvt_pk_bf16_f32 v209, v74, v75
	v_add_co_u32_e32 v72, vcc, s0, v76
	s_nop 1
	v_addc_co_u32_e32 v73, vcc, 0, v77, vcc
	v_mov_b32_e32 v74, v208
	v_mov_b32_e32 v75, v209
	global_store_dwordx2 v[72:73], v[74:75], off
	s_nop 0
	s_nop 0
	v_pk_mul_f32 v[200:201], v[68:69], v[68:69]
	v_pk_mul_f32 v[202:203], v[70:71], v[70:71]
	v_pk_fma_f32 v[200:201], v[200:201], v[204:205], v[206:207] op_sel_hi:[1,0,0]
	v_pk_fma_f32 v[202:203], v[202:203], v[204:205], v[206:207] op_sel_hi:[1,0,0]
	v_pk_mul_f32 v[200:201], v[200:201], v[68:69]
	v_pk_mul_f32 v[202:203], v[202:203], v[70:71]
	v_exp_f32_e32 v200, v200
	v_exp_f32_e32 v201, v201
	v_exp_f32_e32 v202, v202
	v_exp_f32_e32 v203, v203
	s_nop 0
	v_pk_add_f32 v[200:201], v[200:201], 1.0 op_sel_hi:[1,0]
	v_pk_add_f32 v[202:203], v[202:203], 1.0 op_sel_hi:[1,0]
	v_rcp_f32_e32 v200, v200
	v_rcp_f32_e32 v201, v201
	v_rcp_f32_e32 v202, v202
	v_rcp_f32_e32 v203, v203
	s_nop 0
	v_pk_mul_f32 v[68:69], v[68:69], v[200:201]
	v_pk_mul_f32 v[70:71], v[70:71], v[202:203]
	v_cvt_pk_bf16_f32 v208, v68, v69
	v_cvt_pk_bf16_f32 v209, v70, v71
	s_nop 0
	s_nop 0
	v_mov_b32_e32 v68, v208
	v_mov_b32_e32 v69, v209
	global_store_dwordx2 v[76:77], v[68:69], off offset:1024
	s_nop 0
	s_nop 0
	v_pk_mul_f32 v[200:201], v[64:65], v[64:65]
	v_pk_mul_f32 v[202:203], v[66:67], v[66:67]
	v_pk_fma_f32 v[200:201], v[200:201], v[204:205], v[206:207] op_sel_hi:[1,0,0]
	v_pk_fma_f32 v[202:203], v[202:203], v[204:205], v[206:207] op_sel_hi:[1,0,0]
	v_pk_mul_f32 v[200:201], v[200:201], v[64:65]
	v_pk_mul_f32 v[202:203], v[202:203], v[66:67]
	v_exp_f32_e32 v200, v200
	v_exp_f32_e32 v201, v201
	v_exp_f32_e32 v202, v202
	v_exp_f32_e32 v203, v203
	s_nop 0
	v_pk_add_f32 v[200:201], v[200:201], 1.0 op_sel_hi:[1,0]
	v_pk_add_f32 v[202:203], v[202:203], 1.0 op_sel_hi:[1,0]
	v_rcp_f32_e32 v200, v200
	v_rcp_f32_e32 v201, v201
	v_rcp_f32_e32 v202, v202
	v_rcp_f32_e32 v203, v203
	s_nop 0
	v_pk_mul_f32 v[64:65], v[64:65], v[200:201]
	v_pk_mul_f32 v[66:67], v[66:67], v[202:203]
	v_cvt_pk_bf16_f32 v208, v64, v65
	v_cvt_pk_bf16_f32 v209, v66, v67
	s_nop 0
	s_nop 0
	v_mov_b32_e32 v64, v208
	v_mov_b32_e32 v65, v209
	global_store_dwordx2 v[72:73], v[64:65], off offset:1024
	s_mov_b64 s[0:1], 0x200000
	s_nop 0
	s_nop 0
	v_pk_mul_f32 v[200:201], v[60:61], v[60:61]
	v_pk_mul_f32 v[202:203], v[62:63], v[62:63]
	v_pk_fma_f32 v[200:201], v[200:201], v[204:205], v[206:207] op_sel_hi:[1,0,0]
	v_pk_fma_f32 v[202:203], v[202:203], v[204:205], v[206:207] op_sel_hi:[1,0,0]
	v_pk_mul_f32 v[200:201], v[200:201], v[60:61]
	v_pk_mul_f32 v[202:203], v[202:203], v[62:63]
	v_exp_f32_e32 v200, v200
	v_exp_f32_e32 v201, v201
	v_exp_f32_e32 v202, v202
	v_exp_f32_e32 v203, v203
	s_nop 0
	v_pk_add_f32 v[200:201], v[200:201], 1.0 op_sel_hi:[1,0]
	v_pk_add_f32 v[202:203], v[202:203], 1.0 op_sel_hi:[1,0]
	v_rcp_f32_e32 v200, v200
	v_rcp_f32_e32 v201, v201
	v_rcp_f32_e32 v202, v202
	v_rcp_f32_e32 v203, v203
	s_nop 0
	v_pk_mul_f32 v[60:61], v[60:61], v[200:201]
	v_pk_mul_f32 v[62:63], v[62:63], v[202:203]
	v_cvt_pk_bf16_f32 v208, v60, v61
	v_cvt_pk_bf16_f32 v209, v62, v63
	s_nop 0
	s_nop 0
	v_lshl_add_u64 v[60:61], v[124:125], 0, s[0:1]
	s_mov_b32 s0, 0x200000
	v_add_co_u32_e32 v64, vcc, s0, v124
	s_mov_b32 s0, 0x202000
	s_nop 0
	v_addc_co_u32_e32 v65, vcc, 0, v125, vcc
	v_mov_b32_e32 v62, v208
	v_mov_b32_e32 v63, v209
	global_store_dwordx2 v[64:65], v[62:63], off
	s_nop 0
	s_nop 0
	s_nop 0
	s_nop 0
	v_pk_mul_f32 v[200:201], v[56:57], v[56:57]
	v_pk_mul_f32 v[202:203], v[58:59], v[58:59]
	v_pk_fma_f32 v[200:201], v[200:201], v[204:205], v[206:207] op_sel_hi:[1,0,0]
	v_pk_fma_f32 v[202:203], v[202:203], v[204:205], v[206:207] op_sel_hi:[1,0,0]
	v_pk_mul_f32 v[200:201], v[200:201], v[56:57]
	v_pk_mul_f32 v[202:203], v[202:203], v[58:59]
	v_exp_f32_e32 v200, v200
	v_exp_f32_e32 v201, v201
	v_exp_f32_e32 v202, v202
	v_exp_f32_e32 v203, v203
	s_nop 0
	v_pk_add_f32 v[200:201], v[200:201], 1.0 op_sel_hi:[1,0]
	v_pk_add_f32 v[202:203], v[202:203], 1.0 op_sel_hi:[1,0]
	v_rcp_f32_e32 v200, v200
	v_rcp_f32_e32 v201, v201
	v_rcp_f32_e32 v202, v202
	v_rcp_f32_e32 v203, v203
	s_nop 0
	v_pk_mul_f32 v[56:57], v[56:57], v[200:201]
	v_pk_mul_f32 v[58:59], v[58:59], v[202:203]
	v_cvt_pk_bf16_f32 v208, v56, v57
	v_cvt_pk_bf16_f32 v209, v58, v59
	v_add_co_u32_e32 v56, vcc, s0, v124
	s_nop 1
	v_addc_co_u32_e32 v57, vcc, 0, v125, vcc
	v_mov_b32_e32 v58, v208
	v_mov_b32_e32 v59, v209
	global_store_dwordx2 v[56:57], v[58:59], off
	s_nop 0
	s_nop 0
	v_pk_mul_f32 v[200:201], v[52:53], v[52:53]
	v_pk_mul_f32 v[202:203], v[54:55], v[54:55]
	v_pk_fma_f32 v[200:201], v[200:201], v[204:205], v[206:207] op_sel_hi:[1,0,0]
	v_pk_fma_f32 v[202:203], v[202:203], v[204:205], v[206:207] op_sel_hi:[1,0,0]
	v_pk_mul_f32 v[200:201], v[200:201], v[52:53]
	v_pk_mul_f32 v[202:203], v[202:203], v[54:55]
	v_exp_f32_e32 v200, v200
	v_exp_f32_e32 v201, v201
	v_exp_f32_e32 v202, v202
	v_exp_f32_e32 v203, v203
	s_nop 0
	v_pk_add_f32 v[200:201], v[200:201], 1.0 op_sel_hi:[1,0]
	v_pk_add_f32 v[202:203], v[202:203], 1.0 op_sel_hi:[1,0]
	v_rcp_f32_e32 v200, v200
	v_rcp_f32_e32 v201, v201
	v_rcp_f32_e32 v202, v202
	v_rcp_f32_e32 v203, v203
	s_nop 0
	v_pk_mul_f32 v[52:53], v[52:53], v[200:201]
	v_pk_mul_f32 v[54:55], v[54:55], v[202:203]
	v_cvt_pk_bf16_f32 v208, v52, v53
	v_cvt_pk_bf16_f32 v209, v54, v55
	s_nop 0
	s_nop 0
	v_mov_b32_e32 v52, v208
	v_mov_b32_e32 v53, v209
	global_store_dwordx2 v[60:61], v[52:53], off offset:1024
	s_nop 0
	s_nop 0
	v_pk_mul_f32 v[200:201], v[48:49], v[48:49]
	v_pk_mul_f32 v[202:203], v[50:51], v[50:51]
	v_pk_fma_f32 v[200:201], v[200:201], v[204:205], v[206:207] op_sel_hi:[1,0,0]
	v_pk_fma_f32 v[202:203], v[202:203], v[204:205], v[206:207] op_sel_hi:[1,0,0]
	v_pk_mul_f32 v[200:201], v[200:201], v[48:49]
	v_pk_mul_f32 v[202:203], v[202:203], v[50:51]
	v_exp_f32_e32 v200, v200
	v_exp_f32_e32 v201, v201
	v_exp_f32_e32 v202, v202
	v_exp_f32_e32 v203, v203
	s_nop 0
	v_pk_add_f32 v[200:201], v[200:201], 1.0 op_sel_hi:[1,0]
	v_pk_add_f32 v[202:203], v[202:203], 1.0 op_sel_hi:[1,0]
	v_rcp_f32_e32 v200, v200
	v_rcp_f32_e32 v201, v201
	v_rcp_f32_e32 v202, v202
	v_rcp_f32_e32 v203, v203
	s_nop 0
	v_pk_mul_f32 v[48:49], v[48:49], v[200:201]
	v_pk_mul_f32 v[50:51], v[50:51], v[202:203]
	v_cvt_pk_bf16_f32 v208, v48, v49
	v_cvt_pk_bf16_f32 v209, v50, v51
	s_nop 0
	s_nop 0
	v_mov_b32_e32 v48, v208
	v_mov_b32_e32 v49, v209
	global_store_dwordx2 v[56:57], v[48:49], off offset:1024
	s_mov_b64 s[0:1], 0x240000
	s_nop 0
	s_nop 0
	v_pk_mul_f32 v[200:201], v[44:45], v[44:45]
	v_pk_mul_f32 v[202:203], v[46:47], v[46:47]
	v_pk_fma_f32 v[200:201], v[200:201], v[204:205], v[206:207] op_sel_hi:[1,0,0]
	v_pk_fma_f32 v[202:203], v[202:203], v[204:205], v[206:207] op_sel_hi:[1,0,0]
	v_pk_mul_f32 v[200:201], v[200:201], v[44:45]
	v_pk_mul_f32 v[202:203], v[202:203], v[46:47]
	v_exp_f32_e32 v200, v200
	v_exp_f32_e32 v201, v201
	v_exp_f32_e32 v202, v202
	v_exp_f32_e32 v203, v203
	s_nop 0
	v_pk_add_f32 v[200:201], v[200:201], 1.0 op_sel_hi:[1,0]
	v_pk_add_f32 v[202:203], v[202:203], 1.0 op_sel_hi:[1,0]
	v_rcp_f32_e32 v200, v200
	v_rcp_f32_e32 v201, v201
	v_rcp_f32_e32 v202, v202
	v_rcp_f32_e32 v203, v203
	s_nop 0
	v_pk_mul_f32 v[44:45], v[44:45], v[200:201]
	v_pk_mul_f32 v[46:47], v[46:47], v[202:203]
	v_cvt_pk_bf16_f32 v208, v44, v45
	v_cvt_pk_bf16_f32 v209, v46, v47
	s_nop 0
	s_nop 0
	v_lshl_add_u64 v[44:45], v[124:125], 0, s[0:1]
	s_mov_b32 s0, 0x240000
	v_add_co_u32_e32 v48, vcc, s0, v124
	s_mov_b32 s0, 0x242000
	s_nop 0
	v_addc_co_u32_e32 v49, vcc, 0, v125, vcc
	v_mov_b32_e32 v46, v208
	v_mov_b32_e32 v47, v209
	global_store_dwordx2 v[48:49], v[46:47], off
	s_nop 0
	s_nop 0
	s_nop 0
	s_nop 0
	v_pk_mul_f32 v[200:201], v[40:41], v[40:41]
	v_pk_mul_f32 v[202:203], v[42:43], v[42:43]
	v_pk_fma_f32 v[200:201], v[200:201], v[204:205], v[206:207] op_sel_hi:[1,0,0]
	v_pk_fma_f32 v[202:203], v[202:203], v[204:205], v[206:207] op_sel_hi:[1,0,0]
	v_pk_mul_f32 v[200:201], v[200:201], v[40:41]
	v_pk_mul_f32 v[202:203], v[202:203], v[42:43]
	v_exp_f32_e32 v200, v200
	v_exp_f32_e32 v201, v201
	v_exp_f32_e32 v202, v202
	v_exp_f32_e32 v203, v203
	s_nop 0
	v_pk_add_f32 v[200:201], v[200:201], 1.0 op_sel_hi:[1,0]
	v_pk_add_f32 v[202:203], v[202:203], 1.0 op_sel_hi:[1,0]
	v_rcp_f32_e32 v200, v200
	v_rcp_f32_e32 v201, v201
	v_rcp_f32_e32 v202, v202
	v_rcp_f32_e32 v203, v203
	s_nop 0
	v_pk_mul_f32 v[40:41], v[40:41], v[200:201]
	v_pk_mul_f32 v[42:43], v[42:43], v[202:203]
	v_cvt_pk_bf16_f32 v208, v40, v41
	v_cvt_pk_bf16_f32 v209, v42, v43
	v_add_co_u32_e32 v40, vcc, s0, v124
	s_nop 1
	v_addc_co_u32_e32 v41, vcc, 0, v125, vcc
	v_mov_b32_e32 v42, v208
	v_mov_b32_e32 v43, v209
	global_store_dwordx2 v[40:41], v[42:43], off
	s_nop 0
	s_nop 0
	v_pk_mul_f32 v[200:201], v[36:37], v[36:37]
	v_pk_mul_f32 v[202:203], v[38:39], v[38:39]
	v_pk_fma_f32 v[200:201], v[200:201], v[204:205], v[206:207] op_sel_hi:[1,0,0]
	v_pk_fma_f32 v[202:203], v[202:203], v[204:205], v[206:207] op_sel_hi:[1,0,0]
	v_pk_mul_f32 v[200:201], v[200:201], v[36:37]
	v_pk_mul_f32 v[202:203], v[202:203], v[38:39]
	v_exp_f32_e32 v200, v200
	v_exp_f32_e32 v201, v201
	v_exp_f32_e32 v202, v202
	v_exp_f32_e32 v203, v203
	s_nop 0
	v_pk_add_f32 v[200:201], v[200:201], 1.0 op_sel_hi:[1,0]
	v_pk_add_f32 v[202:203], v[202:203], 1.0 op_sel_hi:[1,0]
	v_rcp_f32_e32 v200, v200
	v_rcp_f32_e32 v201, v201
	v_rcp_f32_e32 v202, v202
	v_rcp_f32_e32 v203, v203
	s_nop 0
	v_pk_mul_f32 v[36:37], v[36:37], v[200:201]
	v_pk_mul_f32 v[38:39], v[38:39], v[202:203]
	v_cvt_pk_bf16_f32 v208, v36, v37
	v_cvt_pk_bf16_f32 v209, v38, v39
	s_nop 0
	s_nop 0
	v_mov_b32_e32 v36, v208
	v_mov_b32_e32 v37, v209
	global_store_dwordx2 v[44:45], v[36:37], off offset:1024
	s_nop 0
	s_nop 0
	v_pk_mul_f32 v[200:201], v[32:33], v[32:33]
	v_pk_mul_f32 v[202:203], v[34:35], v[34:35]
	v_pk_fma_f32 v[200:201], v[200:201], v[204:205], v[206:207] op_sel_hi:[1,0,0]
	v_pk_fma_f32 v[202:203], v[202:203], v[204:205], v[206:207] op_sel_hi:[1,0,0]
	v_pk_mul_f32 v[200:201], v[200:201], v[32:33]
	v_pk_mul_f32 v[202:203], v[202:203], v[34:35]
	v_exp_f32_e32 v200, v200
	v_exp_f32_e32 v201, v201
	v_exp_f32_e32 v202, v202
	v_exp_f32_e32 v203, v203
	s_nop 0
	v_pk_add_f32 v[200:201], v[200:201], 1.0 op_sel_hi:[1,0]
	v_pk_add_f32 v[202:203], v[202:203], 1.0 op_sel_hi:[1,0]
	v_rcp_f32_e32 v200, v200
	v_rcp_f32_e32 v201, v201
	v_rcp_f32_e32 v202, v202
	v_rcp_f32_e32 v203, v203
	s_nop 0
	v_pk_mul_f32 v[32:33], v[32:33], v[200:201]
	v_pk_mul_f32 v[34:35], v[34:35], v[202:203]
	v_cvt_pk_bf16_f32 v208, v32, v33
	v_cvt_pk_bf16_f32 v209, v34, v35
	s_nop 0
	s_nop 0
	v_mov_b32_e32 v32, v208
	v_mov_b32_e32 v33, v209
	global_store_dwordx2 v[40:41], v[32:33], off offset:1024
	s_mov_b64 s[0:1], 0x280000
	s_nop 0
	s_nop 0
	v_pk_mul_f32 v[200:201], v[28:29], v[28:29]
	v_pk_mul_f32 v[202:203], v[30:31], v[30:31]
	v_pk_fma_f32 v[200:201], v[200:201], v[204:205], v[206:207] op_sel_hi:[1,0,0]
	v_pk_fma_f32 v[202:203], v[202:203], v[204:205], v[206:207] op_sel_hi:[1,0,0]
	v_pk_mul_f32 v[200:201], v[200:201], v[28:29]
	v_pk_mul_f32 v[202:203], v[202:203], v[30:31]
	v_exp_f32_e32 v200, v200
	v_exp_f32_e32 v201, v201
	v_exp_f32_e32 v202, v202
	v_exp_f32_e32 v203, v203
	s_nop 0
	v_pk_add_f32 v[200:201], v[200:201], 1.0 op_sel_hi:[1,0]
	v_pk_add_f32 v[202:203], v[202:203], 1.0 op_sel_hi:[1,0]
	v_rcp_f32_e32 v200, v200
	v_rcp_f32_e32 v201, v201
	v_rcp_f32_e32 v202, v202
	v_rcp_f32_e32 v203, v203
	s_nop 0
	v_pk_mul_f32 v[28:29], v[28:29], v[200:201]
	v_pk_mul_f32 v[30:31], v[30:31], v[202:203]
	v_cvt_pk_bf16_f32 v208, v28, v29
	v_cvt_pk_bf16_f32 v209, v30, v31
	s_nop 0
	s_nop 0
	v_lshl_add_u64 v[28:29], v[124:125], 0, s[0:1]
	s_mov_b32 s0, 0x280000
	v_add_co_u32_e32 v32, vcc, s0, v124
	s_mov_b32 s0, 0x282000
	s_nop 0
	v_addc_co_u32_e32 v33, vcc, 0, v125, vcc
	v_mov_b32_e32 v30, v208
	v_mov_b32_e32 v31, v209
	global_store_dwordx2 v[32:33], v[30:31], off
	s_nop 0
	s_nop 0
	s_nop 0
	s_nop 0
	v_pk_mul_f32 v[200:201], v[24:25], v[24:25]
	v_pk_mul_f32 v[202:203], v[26:27], v[26:27]
	v_pk_fma_f32 v[200:201], v[200:201], v[204:205], v[206:207] op_sel_hi:[1,0,0]
	v_pk_fma_f32 v[202:203], v[202:203], v[204:205], v[206:207] op_sel_hi:[1,0,0]
	v_pk_mul_f32 v[200:201], v[200:201], v[24:25]
	v_pk_mul_f32 v[202:203], v[202:203], v[26:27]
	v_exp_f32_e32 v200, v200
	v_exp_f32_e32 v201, v201
	v_exp_f32_e32 v202, v202
	v_exp_f32_e32 v203, v203
	s_nop 0
	v_pk_add_f32 v[200:201], v[200:201], 1.0 op_sel_hi:[1,0]
	v_pk_add_f32 v[202:203], v[202:203], 1.0 op_sel_hi:[1,0]
	v_rcp_f32_e32 v200, v200
	v_rcp_f32_e32 v201, v201
	v_rcp_f32_e32 v202, v202
	v_rcp_f32_e32 v203, v203
	s_nop 0
	v_pk_mul_f32 v[24:25], v[24:25], v[200:201]
	v_pk_mul_f32 v[26:27], v[26:27], v[202:203]
	v_cvt_pk_bf16_f32 v208, v24, v25
	v_cvt_pk_bf16_f32 v209, v26, v27
	v_add_co_u32_e32 v24, vcc, s0, v124
	s_nop 1
	v_addc_co_u32_e32 v25, vcc, 0, v125, vcc
	v_mov_b32_e32 v26, v208
	v_mov_b32_e32 v27, v209
	global_store_dwordx2 v[24:25], v[26:27], off
	s_nop 0
	s_nop 0
	v_pk_mul_f32 v[200:201], v[20:21], v[20:21]
	v_pk_mul_f32 v[202:203], v[22:23], v[22:23]
	v_pk_fma_f32 v[200:201], v[200:201], v[204:205], v[206:207] op_sel_hi:[1,0,0]
	v_pk_fma_f32 v[202:203], v[202:203], v[204:205], v[206:207] op_sel_hi:[1,0,0]
	v_pk_mul_f32 v[200:201], v[200:201], v[20:21]
	v_pk_mul_f32 v[202:203], v[202:203], v[22:23]
	v_exp_f32_e32 v200, v200
	v_exp_f32_e32 v201, v201
	v_exp_f32_e32 v202, v202
	v_exp_f32_e32 v203, v203
	s_nop 0
	v_pk_add_f32 v[200:201], v[200:201], 1.0 op_sel_hi:[1,0]
	v_pk_add_f32 v[202:203], v[202:203], 1.0 op_sel_hi:[1,0]
	v_rcp_f32_e32 v200, v200
	v_rcp_f32_e32 v201, v201
	v_rcp_f32_e32 v202, v202
	v_rcp_f32_e32 v203, v203
	s_nop 0
	v_pk_mul_f32 v[20:21], v[20:21], v[200:201]
	v_pk_mul_f32 v[22:23], v[22:23], v[202:203]
	v_cvt_pk_bf16_f32 v208, v20, v21
	v_cvt_pk_bf16_f32 v209, v22, v23
	s_nop 0
	s_nop 0
	v_mov_b32_e32 v20, v208
	v_mov_b32_e32 v21, v209
	global_store_dwordx2 v[28:29], v[20:21], off offset:1024
	s_nop 0
	s_nop 0
	v_pk_mul_f32 v[200:201], v[16:17], v[16:17]
	v_pk_mul_f32 v[202:203], v[18:19], v[18:19]
	v_pk_fma_f32 v[200:201], v[200:201], v[204:205], v[206:207] op_sel_hi:[1,0,0]
	v_pk_fma_f32 v[202:203], v[202:203], v[204:205], v[206:207] op_sel_hi:[1,0,0]
	v_pk_mul_f32 v[200:201], v[200:201], v[16:17]
	v_pk_mul_f32 v[202:203], v[202:203], v[18:19]
	v_exp_f32_e32 v200, v200
	v_exp_f32_e32 v201, v201
	v_exp_f32_e32 v202, v202
	v_exp_f32_e32 v203, v203
	s_nop 0
	v_pk_add_f32 v[200:201], v[200:201], 1.0 op_sel_hi:[1,0]
	v_pk_add_f32 v[202:203], v[202:203], 1.0 op_sel_hi:[1,0]
	v_rcp_f32_e32 v200, v200
	v_rcp_f32_e32 v201, v201
	v_rcp_f32_e32 v202, v202
	v_rcp_f32_e32 v203, v203
	s_nop 0
	v_pk_mul_f32 v[16:17], v[16:17], v[200:201]
	v_pk_mul_f32 v[18:19], v[18:19], v[202:203]
	v_cvt_pk_bf16_f32 v208, v16, v17
	v_cvt_pk_bf16_f32 v209, v18, v19
	s_nop 0
	s_nop 0
	v_mov_b32_e32 v16, v208
	v_mov_b32_e32 v17, v209
	global_store_dwordx2 v[24:25], v[16:17], off offset:1024
	s_mov_b64 s[0:1], 0x2c0000
	s_nop 0
	s_nop 0
	v_pk_mul_f32 v[200:201], v[12:13], v[12:13]
	v_pk_mul_f32 v[202:203], v[14:15], v[14:15]
	v_pk_fma_f32 v[200:201], v[200:201], v[204:205], v[206:207] op_sel_hi:[1,0,0]
	v_pk_fma_f32 v[202:203], v[202:203], v[204:205], v[206:207] op_sel_hi:[1,0,0]
	v_pk_mul_f32 v[200:201], v[200:201], v[12:13]
	v_pk_mul_f32 v[202:203], v[202:203], v[14:15]
	v_exp_f32_e32 v200, v200
	v_exp_f32_e32 v201, v201
	v_exp_f32_e32 v202, v202
	v_exp_f32_e32 v203, v203
	s_nop 0
	v_pk_add_f32 v[200:201], v[200:201], 1.0 op_sel_hi:[1,0]
	v_pk_add_f32 v[202:203], v[202:203], 1.0 op_sel_hi:[1,0]
	v_rcp_f32_e32 v200, v200
	v_rcp_f32_e32 v201, v201
	v_rcp_f32_e32 v202, v202
	v_rcp_f32_e32 v203, v203
	s_nop 0
	v_pk_mul_f32 v[12:13], v[12:13], v[200:201]
	v_pk_mul_f32 v[14:15], v[14:15], v[202:203]
	v_cvt_pk_bf16_f32 v208, v12, v13
	v_cvt_pk_bf16_f32 v209, v14, v15
	s_nop 0
	s_nop 0
	v_lshl_add_u64 v[12:13], v[124:125], 0, s[0:1]
	s_mov_b32 s0, 0x2c0000
	v_add_co_u32_e32 v16, vcc, s0, v124
	s_mov_b32 s0, 0x2c2000
	s_nop 0
	v_addc_co_u32_e32 v17, vcc, 0, v125, vcc
	v_mov_b32_e32 v14, v208
	v_mov_b32_e32 v15, v209
	global_store_dwordx2 v[16:17], v[14:15], off
	s_nop 0
	s_nop 0
	s_nop 0
	s_nop 0
	v_pk_mul_f32 v[200:201], v[8:9], v[8:9]
	v_pk_mul_f32 v[202:203], v[10:11], v[10:11]
	v_pk_fma_f32 v[200:201], v[200:201], v[204:205], v[206:207] op_sel_hi:[1,0,0]
	v_pk_fma_f32 v[202:203], v[202:203], v[204:205], v[206:207] op_sel_hi:[1,0,0]
	v_pk_mul_f32 v[200:201], v[200:201], v[8:9]
	v_pk_mul_f32 v[202:203], v[202:203], v[10:11]
	v_exp_f32_e32 v200, v200
	v_exp_f32_e32 v201, v201
	v_exp_f32_e32 v202, v202
	v_exp_f32_e32 v203, v203
	s_nop 0
	v_pk_add_f32 v[200:201], v[200:201], 1.0 op_sel_hi:[1,0]
	v_pk_add_f32 v[202:203], v[202:203], 1.0 op_sel_hi:[1,0]
	v_rcp_f32_e32 v200, v200
	v_rcp_f32_e32 v201, v201
	v_rcp_f32_e32 v202, v202
	v_rcp_f32_e32 v203, v203
	s_nop 0
	v_pk_mul_f32 v[8:9], v[8:9], v[200:201]
	v_pk_mul_f32 v[10:11], v[10:11], v[202:203]
	v_cvt_pk_bf16_f32 v208, v8, v9
	v_cvt_pk_bf16_f32 v209, v10, v11
	v_add_co_u32_e32 v8, vcc, s0, v124
	s_nop 1
	v_addc_co_u32_e32 v9, vcc, 0, v125, vcc
	v_mov_b32_e32 v10, v208
	v_mov_b32_e32 v11, v209
	global_store_dwordx2 v[8:9], v[10:11], off
	s_nop 0
	s_nop 0
	v_pk_mul_f32 v[200:201], v[4:5], v[4:5]
	v_pk_mul_f32 v[202:203], v[6:7], v[6:7]
	v_pk_fma_f32 v[200:201], v[200:201], v[204:205], v[206:207] op_sel_hi:[1,0,0]
	v_pk_fma_f32 v[202:203], v[202:203], v[204:205], v[206:207] op_sel_hi:[1,0,0]
	v_pk_mul_f32 v[200:201], v[200:201], v[4:5]
	v_pk_mul_f32 v[202:203], v[202:203], v[6:7]
	v_exp_f32_e32 v200, v200
	v_exp_f32_e32 v201, v201
	v_exp_f32_e32 v202, v202
	v_exp_f32_e32 v203, v203
	s_nop 0
	v_pk_add_f32 v[200:201], v[200:201], 1.0 op_sel_hi:[1,0]
	v_pk_add_f32 v[202:203], v[202:203], 1.0 op_sel_hi:[1,0]
	v_rcp_f32_e32 v200, v200
	v_rcp_f32_e32 v201, v201
	v_rcp_f32_e32 v202, v202
	v_rcp_f32_e32 v203, v203
	s_nop 0
	v_pk_mul_f32 v[4:5], v[4:5], v[200:201]
	v_pk_mul_f32 v[6:7], v[6:7], v[202:203]
	v_cvt_pk_bf16_f32 v208, v4, v5
	v_cvt_pk_bf16_f32 v209, v6, v7
	s_nop 0
	s_nop 0
	v_mov_b32_e32 v4, v208
	v_mov_b32_e32 v5, v209
	global_store_dwordx2 v[12:13], v[4:5], off offset:1024
	s_nop 0
	s_nop 0
	v_pk_mul_f32 v[200:201], v[0:1], v[0:1]
	v_pk_mul_f32 v[202:203], v[2:3], v[2:3]
	v_pk_fma_f32 v[200:201], v[200:201], v[204:205], v[206:207] op_sel_hi:[1,0,0]
	v_pk_fma_f32 v[202:203], v[202:203], v[204:205], v[206:207] op_sel_hi:[1,0,0]
	v_pk_mul_f32 v[200:201], v[200:201], v[0:1]
	v_pk_mul_f32 v[202:203], v[202:203], v[2:3]
	v_exp_f32_e32 v200, v200
	v_exp_f32_e32 v201, v201
	v_exp_f32_e32 v202, v202
	v_exp_f32_e32 v203, v203
	s_nop 0
	v_pk_add_f32 v[200:201], v[200:201], 1.0 op_sel_hi:[1,0]
	v_pk_add_f32 v[202:203], v[202:203], 1.0 op_sel_hi:[1,0]
	v_rcp_f32_e32 v200, v200
	v_rcp_f32_e32 v201, v201
	v_rcp_f32_e32 v202, v202
	v_rcp_f32_e32 v203, v203
	s_nop 0
	v_pk_mul_f32 v[0:1], v[0:1], v[200:201]
	v_pk_mul_f32 v[2:3], v[2:3], v[202:203]
	v_cvt_pk_bf16_f32 v208, v0, v1
	v_cvt_pk_bf16_f32 v209, v2, v3
	s_nop 0
	s_nop 0
	v_mov_b32_e32 v0, v208
	v_mov_b32_e32 v1, v209
	global_store_dwordx2 v[8:9], v[0:1], off offset:1024
	s_waitcnt vmcnt(0)
	s_barrier
